# prologue x->bf16 loop: the four loads of a row issued together with counted waits (on top of the mixer rewrites)
# baseline (speedup 1.0000x reference)
.LBB0_47:
	s_waitcnt lgkmcnt(0)
	global_load_dwordx4 v[30:33], v[4:5], off offset:-3072
	global_load_dwordx4 v[34:37], v[4:5], off offset:-2048
	global_load_dwordx4 v[38:41], v[4:5], off offset:-1024
	global_load_dwordx4 v[42:45], v[4:5], off
	v_lshl_add_u64 v[16:17], s[42:43], 0, v[2:3]
	v_add_co_u32_e32 v28, vcc, s18, v16
	s_nop 1
	v_addc_co_u32_e32 v29, vcc, 0, v17, vcc
	s_waitcnt vmcnt(3)
	v_cvt_pk_bf16_f32 v16, v30, v31
	v_cvt_pk_bf16_f32 v17, v32, v33
	global_store_dwordx2 v[28:29], v[16:17], off
	v_mul_f32_e32 v13, v31, v31
	v_mul_f32_e32 v15, v33, v33
	v_fmac_f32_e32 v13, v30, v30
	v_fmac_f32_e32 v15, v32, v32
	v_add_f32_e32 v12, v13, v15
	s_waitcnt vmcnt(3)
	v_cvt_pk_bf16_f32 v20, v34, v35
	v_cvt_pk_bf16_f32 v21, v36, v37
	global_store_dwordx2 v[28:29], v[20:21], off offset:512
	v_mul_f32_e32 v13, v35, v35
	v_mul_f32_e32 v14, v37, v37
	v_fmac_f32_e32 v13, v34, v34
	v_fmac_f32_e32 v14, v36, v36
	v_add_f32_e32 v13, v13, v14
	v_add_f32_e32 v12, v12, v13
	s_waitcnt vmcnt(3)
	v_cvt_pk_bf16_f32 v24, v38, v39
	v_cvt_pk_bf16_f32 v25, v40, v41
	global_store_dwordx2 v[28:29], v[24:25], off offset:1024
	v_mul_f32_e32 v13, v39, v39
	v_mul_f32_e32 v14, v41, v41
	v_fmac_f32_e32 v13, v38, v38
	v_fmac_f32_e32 v14, v40, v40
	v_add_f32_e32 v13, v13, v14
	v_add_f32_e32 v12, v12, v13
	s_waitcnt vmcnt(3)
	v_mul_f32_e32 v13, v43, v43
	v_mul_f32_e32 v14, v45, v45
	v_fmac_f32_e32 v13, v42, v42
	v_fmac_f32_e32 v14, v44, v44
	v_add_f32_e32 v13, v13, v14
	v_add_f32_e32 v12, v12, v13
	ds_bpermute_b32 v13, v6, v12
	v_cvt_pk_bf16_f32 v14, v42, v43
	v_cvt_pk_bf16_f32 v15, v44, v45
	global_store_dwordx2 v[28:29], v[14:15], off offset:1536
	s_waitcnt lgkmcnt(0)
	v_add_f32_e32 v12, v12, v13
	ds_bpermute_b32 v13, v7, v12
	s_waitcnt lgkmcnt(0)
	v_add_f32_e32 v12, v12, v13
	ds_bpermute_b32 v13, v8, v12
	s_waitcnt lgkmcnt(0)
	v_add_f32_e32 v12, v12, v13
	ds_bpermute_b32 v13, v9, v12
	s_waitcnt lgkmcnt(0)
	v_add_f32_e32 v12, v12, v13
	ds_bpermute_b32 v13, v10, v12
	s_waitcnt lgkmcnt(0)
	v_add_f32_e32 v12, v12, v13
	ds_bpermute_b32 v13, v11, v12
	s_and_saveexec_b64 s[16:17], s[6:7]
	s_cbranch_execz .LBB0_46
	s_waitcnt lgkmcnt(0)
	v_add_f32_e32 v12, v12, v13
	v_cndmask_b32_e64 v14, 0, v12, s[4:5]
	v_lshl_add_u64 v[12:13], s[42:43], 0, v[0:1]
	global_store_dword v[12:13], v14, off
	s_branch .LBB0_46
